# grid barriers: non-last arrivers start an L2 write-back before polling (early flush)
# baseline (speedup 1.0000x reference)
.LBB0_88:
	s_or_b64 exec, exec, s[6:7]
	v_cvt_f32_u32_e32 v4, v2
	s_waitcnt vmcnt(0)
	v_readfirstlane_b32 s4, v3
	v_sub_u32_e32 v3, 0, v2
	v_rcp_iflag_f32_e32 v4, v4
	v_add_u32_e32 v5, s4, v1
	v_mul_f32_e32 v4, 0x4f7ffffe, v4
	v_cvt_u32_f32_e32 v4, v4
	v_mul_lo_u32 v1, v3, v4
	v_mul_hi_u32 v1, v4, v1
	v_add_u32_e32 v1, v4, v1
	v_mul_hi_u32 v1, v5, v1
	v_mul_lo_u32 v3, v1, v2
	v_sub_u32_e32 v3, v5, v3
	v_add_u32_e32 v4, 1, v1
	v_cmp_ge_u32_e32 vcc, v3, v2
	s_nop 1
	v_cndmask_b32_e32 v1, v1, v4, vcc
	v_sub_u32_e32 v4, v3, v2
	v_cndmask_b32_e32 v3, v3, v4, vcc
	v_add_u32_e32 v4, 1, v1
	v_cmp_ge_u32_e32 vcc, v3, v2
	v_add_u32_e32 v3, 1, v5
	s_nop 0
	v_cndmask_b32_e32 v1, v1, v4, vcc
	v_mul_lo_u32 v4, v2, v1
	v_add_u32_e32 v2, v4, v2
	v_cmp_ne_u32_e32 vcc, v3, v2
	s_and_saveexec_b64 s[4:5], vcc
	s_xor_b64 s[4:5], exec, s[4:5]
	s_cbranch_execz .LBB0_102
	s_waitcnt lgkmcnt(0)
	buffer_wbl2 sc1
	v_mov_b32_e32 v0, 0x2000
	global_load_dword v0, v0, s[2:3] offset:1024 sc1
	s_add_u32 s8, s2, 0x2400
	s_addc_u32 s9, s3, 0
	s_waitcnt vmcnt(0)
	v_cmp_eq_u32_e32 vcc, v0, v1
	s_and_saveexec_b64 s[6:7], vcc
	s_cbranch_execz .LBB0_101
	s_mov_b32 s20, 1
	s_mov_b64 s[10:11], 0
	v_mov_b32_e32 v0, 0
	s_branch .LBB0_92

.LBB0_437:
	s_or_b64 exec, exec, s[6:7]
	v_cvt_f32_u32_e32 v4, v2
	s_waitcnt vmcnt(0)
	v_readfirstlane_b32 s4, v3
	v_sub_u32_e32 v3, 0, v2
	v_rcp_iflag_f32_e32 v4, v4
	v_add_u32_e32 v5, s4, v1
	v_mul_f32_e32 v4, 0x4f7ffffe, v4
	v_cvt_u32_f32_e32 v4, v4
	v_mul_lo_u32 v1, v3, v4
	v_mul_hi_u32 v1, v4, v1
	v_add_u32_e32 v1, v4, v1
	v_mul_hi_u32 v1, v5, v1
	v_mul_lo_u32 v3, v1, v2
	v_sub_u32_e32 v3, v5, v3
	v_add_u32_e32 v4, 1, v1
	v_cmp_ge_u32_e32 vcc, v3, v2
	s_nop 1
	v_cndmask_b32_e32 v1, v1, v4, vcc
	v_sub_u32_e32 v4, v3, v2
	v_cndmask_b32_e32 v3, v3, v4, vcc
	v_add_u32_e32 v4, 1, v1
	v_cmp_ge_u32_e32 vcc, v3, v2
	v_add_u32_e32 v3, 1, v5
	s_nop 0
	v_cndmask_b32_e32 v1, v1, v4, vcc
	v_mul_lo_u32 v4, v2, v1
	v_add_u32_e32 v2, v4, v2
	v_cmp_ne_u32_e32 vcc, v3, v2
	s_and_saveexec_b64 s[4:5], vcc
	s_xor_b64 s[4:5], exec, s[4:5]
	s_cbranch_execz .LBB0_451
	s_waitcnt lgkmcnt(0)
	buffer_wbl2 sc1
	v_mov_b32_e32 v0, 0x2000
	global_load_dword v0, v0, s[2:3] offset:1024 sc1
	s_add_u32 s8, s2, 0x2400
	s_addc_u32 s9, s3, 0
	s_waitcnt vmcnt(0)
	v_cmp_eq_u32_e32 vcc, v0, v1
	s_and_saveexec_b64 s[6:7], vcc
	s_cbranch_execz .LBB0_450
	s_mov_b32 s30, 1
	s_mov_b64 s[10:11], 0
	v_mov_b32_e32 v0, 0
	s_branch .LBB0_441

.LBB0_542:
	s_or_b64 exec, exec, s[6:7]
	v_cvt_f32_u32_e32 v4, v2
	s_waitcnt vmcnt(0)
	v_readfirstlane_b32 s4, v3
	v_sub_u32_e32 v3, 0, v2
	v_rcp_iflag_f32_e32 v4, v4
	v_add_u32_e32 v5, s4, v1
	v_mul_f32_e32 v4, 0x4f7ffffe, v4
	v_cvt_u32_f32_e32 v4, v4
	v_mul_lo_u32 v1, v3, v4
	v_mul_hi_u32 v1, v4, v1
	v_add_u32_e32 v1, v4, v1
	v_mul_hi_u32 v1, v5, v1
	v_mul_lo_u32 v3, v1, v2
	v_sub_u32_e32 v3, v5, v3
	v_add_u32_e32 v4, 1, v1
	v_cmp_ge_u32_e32 vcc, v3, v2
	s_nop 1
	v_cndmask_b32_e32 v1, v1, v4, vcc
	v_sub_u32_e32 v4, v3, v2
	v_cndmask_b32_e32 v3, v3, v4, vcc
	v_add_u32_e32 v4, 1, v1
	v_cmp_ge_u32_e32 vcc, v3, v2
	v_add_u32_e32 v3, 1, v5
	s_nop 0
	v_cndmask_b32_e32 v1, v1, v4, vcc
	v_mul_lo_u32 v4, v2, v1
	v_add_u32_e32 v2, v4, v2
	v_cmp_ne_u32_e32 vcc, v3, v2
	s_and_saveexec_b64 s[4:5], vcc
	s_xor_b64 s[4:5], exec, s[4:5]
	s_cbranch_execz .LBB0_556
	s_waitcnt lgkmcnt(0)
	buffer_wbl2 sc1
	v_mov_b32_e32 v0, 0x2000
	global_load_dword v0, v0, s[2:3] offset:1024 sc1
	s_add_u32 s8, s2, 0x2400
	s_addc_u32 s9, s3, 0
	s_waitcnt vmcnt(0)
	v_cmp_eq_u32_e32 vcc, v0, v1
	s_and_saveexec_b64 s[6:7], vcc
	s_cbranch_execz .LBB0_555
	s_mov_b32 s28, 1
	s_mov_b64 s[10:11], 0
	v_mov_b32_e32 v0, 0
	s_branch .LBB0_546
